# prologue phase: x to bf16 conversion issues 16 row loads per wave before converting, instead of one row per loop trip with a kernarg reload
# baseline (speedup 1.0000x reference)
.LBB0_39:
	s_or_b64 exec, exec, s[6:7]
	v_lshl_add_u32 v4, s2, 9, v166
	s_mov_b32 s3, 0x210000
	s_lshl_b32 s6, s33, 9
	v_cmp_gt_i32_e32 vcc, s3, v4
	s_and_saveexec_b64 s[8:9], vcc
	s_cbranch_execz .LBB0_46
	s_load_dwordx16 s[36:51], s[0:1], 0x0
	s_add_u32 s10, s94, 0x6a00000
	s_addc_u32 s11, s95, 0
	v_lshrrev_b32_e32 v0, 8, v166
	v_lshl_add_u32 v0, s2, 1, v0
	v_lshlrev_b32_e32 v1, 3, v166
	v_and_b32_e32 v1, 0x7f8, v1
	v_lshlrev_b32_e32 v2, 13, v0
	v_lshl_add_u32 v2, v1, 2, v2
	v_lshlrev_b32_e32 v3, 12, v0
	v_lshl_add_u32 v3, v1, 1, v3
	s_waitcnt lgkmcnt(0)
	s_mov_b64 s[12:13], s[36:37]
	s_mov_b64 s[14:15], s[10:11]
	s_mov_b32 s16, 0
.Lp0b_batch:
	global_load_dwordx4 v[32:35], v2, s[12:13]
	global_load_dwordx4 v[36:39], v2, s[12:13] offset:16
	s_add_u32 s12, s12, 0x400000
	s_addc_u32 s13, s13, 0
	global_load_dwordx4 v[40:43], v2, s[12:13]
	global_load_dwordx4 v[44:47], v2, s[12:13] offset:16
	s_add_u32 s12, s12, 0x400000
	s_addc_u32 s13, s13, 0
	global_load_dwordx4 v[48:51], v2, s[12:13]
	global_load_dwordx4 v[52:55], v2, s[12:13] offset:16
	s_add_u32 s12, s12, 0x400000
	s_addc_u32 s13, s13, 0
	global_load_dwordx4 v[56:59], v2, s[12:13]
	global_load_dwordx4 v[60:63], v2, s[12:13] offset:16
	s_add_u32 s12, s12, 0x400000
	s_addc_u32 s13, s13, 0
	global_load_dwordx4 v[64:67], v2, s[12:13]
	global_load_dwordx4 v[68:71], v2, s[12:13] offset:16
	s_add_u32 s12, s12, 0x400000
	s_addc_u32 s13, s13, 0
	global_load_dwordx4 v[72:75], v2, s[12:13]
	global_load_dwordx4 v[76:79], v2, s[12:13] offset:16
	s_add_u32 s12, s12, 0x400000
	s_addc_u32 s13, s13, 0
	global_load_dwordx4 v[80:83], v2, s[12:13]
	global_load_dwordx4 v[84:87], v2, s[12:13] offset:16
	s_add_u32 s12, s12, 0x400000
	s_addc_u32 s13, s13, 0
	global_load_dwordx4 v[88:91], v2, s[12:13]
	global_load_dwordx4 v[92:95], v2, s[12:13] offset:16
	s_add_u32 s12, s12, 0x400000
	s_addc_u32 s13, s13, 0
	s_waitcnt vmcnt(14)
	v_cvt_pk_bf16_f32 v12, v32, v33
	v_cvt_pk_bf16_f32 v13, v34, v35
	v_cvt_pk_bf16_f32 v14, v36, v37
	v_cvt_pk_bf16_f32 v15, v38, v39
	global_store_dwordx4 v3, v[12:15], s[14:15]
	s_add_u32 s14, s14, 0x200000
	s_addc_u32 s15, s15, 0
	s_waitcnt vmcnt(13)
	v_cvt_pk_bf16_f32 v16, v40, v41
	v_cvt_pk_bf16_f32 v17, v42, v43
	v_cvt_pk_bf16_f32 v18, v44, v45
	v_cvt_pk_bf16_f32 v19, v46, v47
	global_store_dwordx4 v3, v[16:19], s[14:15]
	s_add_u32 s14, s14, 0x200000
	s_addc_u32 s15, s15, 0
	s_waitcnt vmcnt(12)
	v_cvt_pk_bf16_f32 v12, v48, v49
	v_cvt_pk_bf16_f32 v13, v50, v51
	v_cvt_pk_bf16_f32 v14, v52, v53
	v_cvt_pk_bf16_f32 v15, v54, v55
	global_store_dwordx4 v3, v[12:15], s[14:15]
	s_add_u32 s14, s14, 0x200000
	s_addc_u32 s15, s15, 0
	s_waitcnt vmcnt(11)
	v_cvt_pk_bf16_f32 v16, v56, v57
	v_cvt_pk_bf16_f32 v17, v58, v59
	v_cvt_pk_bf16_f32 v18, v60, v61
	v_cvt_pk_bf16_f32 v19, v62, v63
	global_store_dwordx4 v3, v[16:19], s[14:15]
	s_add_u32 s14, s14, 0x200000
	s_addc_u32 s15, s15, 0
	s_waitcnt vmcnt(10)
	v_cvt_pk_bf16_f32 v12, v64, v65
	v_cvt_pk_bf16_f32 v13, v66, v67
	v_cvt_pk_bf16_f32 v14, v68, v69
	v_cvt_pk_bf16_f32 v15, v70, v71
	global_store_dwordx4 v3, v[12:15], s[14:15]
	s_add_u32 s14, s14, 0x200000
	s_addc_u32 s15, s15, 0
	s_waitcnt vmcnt(9)
	v_cvt_pk_bf16_f32 v16, v72, v73
	v_cvt_pk_bf16_f32 v17, v74, v75
	v_cvt_pk_bf16_f32 v18, v76, v77
	v_cvt_pk_bf16_f32 v19, v78, v79
	global_store_dwordx4 v3, v[16:19], s[14:15]
	s_add_u32 s14, s14, 0x200000
	s_addc_u32 s15, s15, 0
	s_waitcnt vmcnt(8)
	v_cvt_pk_bf16_f32 v12, v80, v81
	v_cvt_pk_bf16_f32 v13, v82, v83
	v_cvt_pk_bf16_f32 v14, v84, v85
	v_cvt_pk_bf16_f32 v15, v86, v87
	global_store_dwordx4 v3, v[12:15], s[14:15]
	s_add_u32 s14, s14, 0x200000
	s_addc_u32 s15, s15, 0
	s_waitcnt vmcnt(7)
	v_cvt_pk_bf16_f32 v16, v88, v89
	v_cvt_pk_bf16_f32 v17, v90, v91
	v_cvt_pk_bf16_f32 v18, v92, v93
	v_cvt_pk_bf16_f32 v19, v94, v95
	global_store_dwordx4 v3, v[16:19], s[14:15]
	s_add_u32 s14, s14, 0x200000
	s_addc_u32 s15, s15, 0
	s_add_i32 s16, s16, 1
	s_cmp_lt_u32 s16, 2
	s_cbranch_scc1 .Lp0b_batch
	v_readfirstlane_b32 s17, v0
	s_cmp_gt_u32 s17, 0xff
	s_cbranch_scc1 .LBB0_46
	v_mov_b32_e32 v12, 0
	v_mov_b32_e32 v13, 0
	v_mov_b32_e32 v14, 0
	v_mov_b32_e32 v15, 0
	s_cmp_gt_u32 s17, 0x7f
	s_cbranch_scc1 .Lp0b_st
	global_load_dwordx4 v[32:35], v2, s[38:39]
	global_load_dwordx4 v[36:39], v2, s[38:39] offset:16
	s_waitcnt vmcnt(0)
	v_cvt_pk_bf16_f32 v12, v32, v33
	v_cvt_pk_bf16_f32 v13, v34, v35
	v_cvt_pk_bf16_f32 v14, v36, v37
	v_cvt_pk_bf16_f32 v15, v38, v39
.Lp0b_st:
	global_store_dwordx4 v3, v[12:15], s[14:15]
